# down GEMM walks each XCD's row tiles newest-first (reverse of the order the gate/up GEMM wrote the hidden activations) for memory-side cache hits
# speedup vs baseline: 1.0042x; 1.0031x over previous
.LBB0_9:
	s_ashr_i32 s73, s2, 31
	v_writelane_b32 v253, s4, 4
	s_lshr_b32 s4, s73, 29
	s_add_i32 s4, s2, s4
	s_ashr_i32 s22, s4, 3
	s_and_b32 s4, s4, -8
	s_sub_i32 s23, s2, s4
	s_add_u32 s62, s0, 0x4200
	s_addc_u32 s63, s1, 0
	s_add_u32 s4, s0, 0x4400
	s_addc_u32 s5, s1, 0
	v_writelane_b32 v253, s4, 5
	s_load_dword s24, s[60:61], 0xd0
	v_mov_b32_e32 v189, 0
	v_writelane_b32 v253, s5, 6
	s_add_u32 s4, s0, 0x4500
	s_addc_u32 s5, s1, 0
	v_writelane_b32 v253, s4, 7
	v_mov_b32_e32 v214, 0x3c0881c4
	v_mov_b32_e32 v215, 0xbab64f3b
	v_writelane_b32 v253, s5, 8
	s_add_u32 s4, s0, 0x4600
	s_addc_u32 s5, s1, 0
	v_writelane_b32 v253, s4, 9
	v_mov_b32_e32 v191, 0x3727c5ac
	v_mov_b32_e32 v216, 0x260
	v_writelane_b32 v253, s5, 10
	s_add_u32 s4, s0, 0x4700
	s_addc_u32 s5, s1, 0
	v_writelane_b32 v253, s4, 11
	v_mov_b32_e32 v227, 1
	v_mov_b32_e32 v252, 0xc0135761
	v_writelane_b32 v253, s5, 12
	s_add_u32 s4, s0, 0x4800
	s_addc_u32 s5, s1, 0
	s_add_u32 s68, s0, 0x4900
	v_writelane_b32 v253, s4, 13
	s_addc_u32 s69, s1, 0
	v_mov_b32_e32 v190, 0x43dc0000
	v_writelane_b32 v253, s5, 14
	s_add_u32 s4, s0, 0x4a00
	s_addc_u32 s5, s1, 0
	s_add_u32 s6, s0, 0x4b00
	s_addc_u32 s7, s1, 0
	s_add_u32 s8, s0, 0x4c00
	s_addc_u32 s9, s1, 0
	s_add_u32 s10, s0, 0x4d00
	s_addc_u32 s11, s1, 0
	s_add_u32 s12, s0, 0x4e00
	s_addc_u32 s13, s1, 0
	s_add_u32 s88, s0, 0x4f00
	s_addc_u32 s89, s1, 0
	s_add_u32 s90, s0, 0x5000
	s_addc_u32 s91, s1, 0
	s_add_u32 s92, s0, 0x5100
	s_addc_u32 s93, s1, 0
	s_add_u32 s94, s0, 0x5200
	s_addc_u32 s95, s1, 0
	s_add_u32 s96, s0, 0x5300
	s_addc_u32 s97, s1, 0
	s_cmp_eq_u32 s3, 15
	s_cselect_b64 s[16:17], -1, 0
	v_writelane_b32 v253, s16, 15
	s_cmp_eq_u32 s3, 14
	v_mov_b32_e32 v217, 0x7f800000
	v_writelane_b32 v253, s17, 16
	s_cselect_b64 s[16:17], -1, 0
	v_writelane_b32 v253, s16, 17
	s_cmp_eq_u32 s3, 13
	v_mov_b32_e32 v219, 0x7fc00000
	v_writelane_b32 v253, s17, 18
	s_cselect_b64 s[16:17], -1, 0
	v_writelane_b32 v253, s16, 19
	s_cmp_eq_u32 s3, 12
	v_mov_b32_e32 v218, 0x3c800000
	v_writelane_b32 v253, s17, 20
	s_cselect_b64 s[16:17], -1, 0
	v_writelane_b32 v253, s16, 21
	s_cmp_eq_u32 s3, 11
	v_mov_b32_e32 v193, 0x10000
	v_writelane_b32 v253, s17, 22
	s_cselect_b64 s[16:17], -1, 0
	v_writelane_b32 v253, s16, 23
	s_cmp_eq_u32 s3, 10
	s_mov_b32 s87, 0x8000
	v_writelane_b32 v253, s17, 24
	s_cselect_b64 s[16:17], -1, 0
	v_writelane_b32 v253, s16, 25
	s_cmp_eq_u32 s3, 9
	s_movk_i32 s33, 0x7fff
	v_writelane_b32 v253, s17, 26
	s_cselect_b64 s[16:17], -1, 0
	v_writelane_b32 v253, s16, 27
	s_cmp_eq_u32 s3, 8
	s_movk_i32 s85, 0x3dff
	v_writelane_b32 v253, s17, 28
	s_cselect_b64 s[16:17], -1, 0
	v_writelane_b32 v253, s16, 29
	s_cmp_eq_u32 s3, 7
	s_mov_b32 s65, 0
	v_writelane_b32 v253, s17, 30
	s_cselect_b64 s[16:17], -1, 0
	v_writelane_b32 v253, s16, 31
	s_cmp_eq_u32 s3, 6
	s_mov_b64 s[28:29], 0x100000
	v_writelane_b32 v253, s17, 32
	s_cselect_b64 s[16:17], -1, 0
	v_writelane_b32 v253, s16, 33
	s_cmp_eq_u32 s3, 5
	s_mov_b64 s[30:31], 0x80
	v_writelane_b32 v253, s17, 34
	s_cselect_b64 s[16:17], -1, 0
	v_writelane_b32 v253, s16, 35
	s_cmp_eq_u32 s3, 4
	s_mov_b64 s[34:35], 0x40080
	v_writelane_b32 v253, s17, 36
	s_cselect_b64 s[16:17], -1, 0
	v_writelane_b32 v253, s16, 37
	s_cmp_eq_u32 s3, 3
	s_mov_b32 s72, 0x3c800000
	v_writelane_b32 v253, s17, 38
	s_cselect_b64 s[16:17], -1, 0
	v_writelane_b32 v253, s16, 39
	s_cmp_eq_u32 s3, 2
	s_mov_b64 s[82:83], 0x800
	v_writelane_b32 v253, s17, 40
	s_cselect_b64 s[16:17], -1, 0
	v_writelane_b32 v253, s16, 41
	s_cmp_eq_u32 s3, 1
	s_mov_b32 s70, 0xffff
	v_writelane_b32 v253, s17, 42
	s_cselect_b64 s[16:17], -1, 0
	v_writelane_b32 v253, s16, 43
	s_cmp_eq_u32 s3, 0
	s_nop 0
	v_writelane_b32 v253, s17, 44
	s_cselect_b64 s[16:17], -1, 0
	s_lshl_b32 s3, s3, 8
	s_add_u32 s3, s14, s3
	v_writelane_b32 v253, s16, 45
	s_addc_u32 s14, s15, 0
	s_nop 0
	v_writelane_b32 v253, s17, 46
	s_add_u32 s16, s3, 0x1400
	s_addc_u32 s17, s14, 0
	v_writelane_b32 v253, s16, 47
	s_nop 1
	v_writelane_b32 v253, s17, 48
	s_add_u32 s16, s3, 0x2400
	s_addc_u32 s17, s14, 0
	v_writelane_b32 v253, s16, 49
	s_add_u32 s14, s0, 0x7400
	s_addc_u32 s15, s1, 0
	v_writelane_b32 v253, s17, 50
	v_writelane_b32 v253, s14, 51
	s_add_u32 s0, s0, 0x7500
	s_addc_u32 s1, s1, 0
	v_writelane_b32 v253, s15, 52
	v_writelane_b32 v253, s0, 53
	s_cmpk_gt_i32 s2, 0x9ff
	s_movk_i32 s16, 0x501
	v_writelane_b32 v253, s1, 54
	s_cselect_b64 s[0:1], -1, 0
	v_writelane_b32 v253, s0, 55
	s_bfe_u32 s3, s2, 0x30003
	s_nop 0
	v_writelane_b32 v253, s1, 56
	s_and_b32 s1, s2, 7
	s_mul_i32 s0, s1, 40
	s_or_b32 s0, s3, s0
	v_writelane_b32 v253, s0, 57
	s_bfe_u32 s0, s2, 0x20006
	v_writelane_b32 v253, s0, 58
	s_and_b32 s0, s2, 56
	s_cmpk_lt_i32 s2, 0x500
	v_writelane_b32 v253, s0, 59
	s_cselect_b64 s[14:15], -1, 0
	v_writelane_b32 v253, s14, 60
	s_cmp_lt_u32 s2, 32
	s_mulk_i32 s1, 0x140
	v_writelane_b32 v253, s15, 61
	s_cselect_b64 s[14:15], -1, 0
	s_and_b32 s3, s2, 15
	v_writelane_b32 v253, s14, 62
	s_cmp_gt_u32 s2, 15
	s_nop 0
	v_writelane_b32 v253, s15, 63
	s_cselect_b64 s[14:15], -1, 0
	v_writelane_b32 v254, s14, 0
	s_lshl_b32 s0, s3, 13
	s_add_i32 s0, s0, 0x8000
	v_writelane_b32 v254, s15, 1
	v_writelane_b32 v254, s0, 2
	s_waitcnt lgkmcnt(0)
	s_lshl_b32 s0, s24, 3
	s_addk_i32 s0, 0xff00
	v_writelane_b32 v254, s0, 3
	s_lshl_b32 s14, s2, 11
	v_writelane_b32 v254, s14, 4
	s_lshl_b32 s14, s2, 3
	s_lshl_b32 s74, s2, 14
	s_lshl_b32 s0, s3, 16
	v_writelane_b32 v254, s14, 5
	s_addk_i32 s14, 0xff00
	s_cmpk_lt_i32 s2, 0x2800
	v_writelane_b32 v254, s14, 6
	s_cselect_b64 s[14:15], -1, 0
	v_writelane_b32 v254, s14, 7
	s_cmpk_lt_i32 s2, 0xa00
	s_nop 0
	v_writelane_b32 v254, s15, 8
	s_cselect_b64 s[14:15], -1, 0
	v_writelane_b32 v254, s14, 9
	s_cmp_lt_i32 s23, 0
	s_cselect_b32 s16, s16, 0x500
	v_writelane_b32 v254, s15, 10
	s_movk_i32 s14, 0x141
	s_cselect_b32 s14, s14, 0x140
	s_mul_i32 s14, s23, s14
	s_movk_i32 s15, 0xa1
	s_cselect_b32 s15, s15, 0xa0
	s_add_i32 s17, s14, s22
	s_ashr_i32 s18, s17, 31
	s_lshr_b32 s14, s18, 26
	s_add_i32 s14, s17, s14
	s_and_b32 s19, s14, 0xffc0
	s_sub_i32 s19, s17, s19
	s_bfe_i32 s20, s19, 0x80000
	s_bfe_u32 s20, s20, 0x3000c
	s_add_i32 s20, s19, s20
	s_and_b32 s21, s20, 0xf8
	s_sub_i32 s19, s19, s21
	s_ashr_i32 s14, s14, 6
	s_lshl_b32 s14, s14, 3
	s_sext_i32_i8 s19, s19
	s_add_i32 s14, s14, s19
	v_writelane_b32 v254, s14, 11
	s_mul_i32 s14, s23, s15
	s_add_i32 s14, s14, s22
	s_ashr_i32 s15, s14, 31
	s_lshr_b32 s15, s15, 27
	s_add_i32 s15, s14, s15
	s_and_b32 s19, s15, 0xffe0
	s_sub_i32 s14, s14, s19
	s_bfe_i32 s19, s14, 0x80000
	s_bfe_u32 s19, s19, 0x3000c
	s_add_i32 s19, s14, s19
	s_mul_i32 s16, s23, s16
	s_and_b32 s21, s19, 0xf8
	s_add_i32 s16, s16, s22
	s_sub_i32 s14, s14, s21
	s_ashr_i32 s21, s16, 31
	s_lshr_b32 s21, s21, 25
	s_bfe_i32 s20, s20, 0x80000
	v_writelane_b32 v254, s23, 12
	s_add_i32 s21, s16, s21
	s_sext_i32_i16 s20, s20
	s_ashr_i32 s15, s15, 5
	s_bfe_i32 s19, s19, 0x80000
	v_writelane_b32 v254, s22, 13
	s_and_b32 s22, s21, 0xff80
	s_ashr_i32 s20, s20, 3
	s_lshl_b32 s15, s15, 3
	s_sext_i32_i16 s19, s19
	s_sext_i32_i8 s14, s14
	s_sub_i32 s16, s16, s22
	v_writelane_b32 v254, s20, 14
	s_add_i32 s26, s15, s14
	s_ashr_i32 s14, s19, 3
	s_bfe_i32 s22, s16, 0x80000
	v_writelane_b32 v254, s14, 15
	s_lshr_b32 s14, s19, 3
	s_bfe_u32 s22, s22, 0x3000c
	s_bfe_i64 s[14:15], s[14:15], 0x100000
	s_add_i32 s22, s16, s22
	s_lshl_b64 s[14:15], s[14:15], 19
	s_and_b32 s23, s22, 0xf8
	v_writelane_b32 v254, s14, 16
	s_sub_i32 s16, s16, s23
	s_sext_i32_i8 s16, s16
	v_writelane_b32 v254, s15, 17
	s_ashr_i32 s14, s21, 7
	s_bfe_i32 s15, s22, 0x80000
	s_lshl_b32 s14, s14, 3
	s_sext_i32_i16 s15, s15
	s_add_i32 s20, s14, s16
	s_ashr_i32 s14, s15, 3
	v_writelane_b32 v254, s14, 18
	s_lshr_b32 s14, s15, 3
	s_bfe_i64 s[14:15], s[14:15], 0x100000
	s_lshl_b64 s[14:15], s[14:15], 18
	v_writelane_b32 v254, s14, 19
	s_ashr_i32 s27, s26, 31
	s_lshl_b64 s[22:23], s[26:27], 19
	v_writelane_b32 v254, s15, 20
	s_add_i32 s14, s20, 0xffffff80
	s_lshr_b32 s14, s14, 5
	s_ashr_i32 s15, s20, 3
	s_mov_b32 s16, s26
	s_cmpk_lt_i32 s20, 0x80
	v_writelane_b32 v254, s16, 21
	s_cselect_b32 s14, s15, s14
	s_lshr_b32 s15, s18, 27
	v_writelane_b32 v254, s17, 22
	s_add_i32 s16, s17, s15
	s_and_b32 s15, s16, 0xffe0
	s_sub_i32 s15, s17, s15
	s_bfe_i32 s17, s15, 0x80000
	s_bfe_u32 s17, s17, 0x3000c
	v_writelane_b32 v254, s22, 23
	s_add_i32 s17, s15, s17
	s_and_b32 s18, s17, 0xf8
	v_writelane_b32 v254, s23, 24
	s_sub_i32 s18, s15, s18
	v_writelane_b32 v254, s1, 25
	s_mul_i32 s1, s3, 0x14000
	s_ashr_i32 s15, s14, 31
	v_writelane_b32 v254, s1, 26
	s_lshl_b64 s[14:15], s[14:15], 22
	v_writelane_b32 v254, s14, 27
	s_ashr_i32 s1, s16, 5
	s_bfe_i32 s3, s17, 0x80000
	v_writelane_b32 v254, s15, 28
	s_lshl_b32 s1, s1, 3
	s_sext_i32_i16 s3, s3
	s_sext_i32_i8 s14, s18
	s_add_i32 s16, s1, s14
	s_mul_i32 s98, s16, 0xcccd
	s_lshr_b32 s98, s98, 22
	s_mul_i32 s98, s98, 0xa0
	s_addk_i32 s98, 0x4f
	s_sub_i32 s16, s98, s16
	s_lshr_b32 s14, s3, 3
	s_ashr_i32 s1, s3, 3
	s_bfe_i64 s[14:15], s[14:15], 0x100000
	v_writelane_b32 v254, s1, 29
	s_lshl_b64 s[14:15], s[14:15], 19
	v_writelane_b32 v254, s14, 30
	s_ashr_i32 s21, s20, 31
	s_ashr_i32 s17, s16, 31
	v_writelane_b32 v254, s15, 31
	s_mov_b32 s14, s20
	v_writelane_b32 v254, s14, 32
	s_add_i32 s1, s16, 0xffffff80
	s_lshr_b32 s1, s1, 5
	v_writelane_b32 v254, s15, 33
	s_lshl_b64 s[14:15], s[20:21], 10
	v_writelane_b32 v254, s14, 34
	s_ashr_i32 s3, s16, 3
	s_mov_b64 s[26:27], 0x40000
	v_writelane_b32 v254, s15, 35
	s_lshl_b64 s[14:15], s[16:17], 19
	v_writelane_b32 v254, s14, 36
	s_cmpk_lt_i32 s16, 0x80
	s_mov_b64 s[20:21], 0xc0000
	v_writelane_b32 v254, s15, 37
	s_mov_b32 s14, s16
	v_writelane_b32 v254, s14, 38
	v_cmp_eq_u32_e64 s[16:17], 0, v0
	s_mov_b64 s[22:23], 0x80000
	v_writelane_b32 v254, s15, 39
	s_cselect_b32 s14, s3, s1
	s_ashr_i32 s15, s14, 31
	s_lshl_b64 s[14:15], s[14:15], 21
	v_writelane_b32 v254, s14, 40
	s_lshl_b32 s1, s24, 8
	s_addk_i32 s1, 0xe000
	v_writelane_b32 v254, s15, 41
	v_writelane_b32 v254, s1, 42
	s_lshl_b32 s1, s24, 4
	s_addk_i32 s1, 0xfe00
	v_writelane_b32 v254, s1, 43
	s_lshl_b32 s1, s24, 10
	s_addk_i32 s1, 0x8000
	v_writelane_b32 v254, s1, 44
	s_lshl_b32 s0, s0, 2
	v_writelane_b32 v254, s0, 45
	s_add_i32 s0, 0, 0x12200
	v_writelane_b32 v254, s0, 46
	s_add_i32 s0, 0, 0x11200
	v_writelane_b32 v254, s0, 47
	s_add_i32 s0, 0, 0x10200
	v_writelane_b32 v254, s0, 48
	s_add_i32 s0, 0, 0x10004
	v_writelane_b32 v254, s0, 49
	s_add_i32 s0, 0, 0x10008
	v_writelane_b32 v254, s0, 50
	s_add_i32 s0, 0, 0x1000c
	v_writelane_b32 v254, s0, 51
	s_add_i32 s0, 0, 0x10010
	v_writelane_b32 v254, s0, 52
	s_add_i32 s0, 0, 0x10014
	v_writelane_b32 v254, s0, 53
	s_add_i32 s0, 0, 0x10018
	v_writelane_b32 v254, s0, 54
	s_add_i32 s0, 0, 0x1001c
	v_writelane_b32 v254, s0, 55
	s_add_i32 s0, 0, 0x10040
	v_writelane_b32 v254, s0, 56
	s_add_i32 s0, 0, 0x10020
	v_writelane_b32 v254, s0, 57
	s_add_i32 s0, 0, 0x10024
	v_writelane_b32 v254, s0, 58
	s_add_i32 s0, 0, 0x10028
	v_writelane_b32 v254, s0, 59
	s_add_i32 s0, 0, 0x1002c
	v_writelane_b32 v254, s0, 60
	s_add_i32 s0, 0, 0x10030
	v_writelane_b32 v254, s0, 61
	s_add_i32 s0, 0, 0x10034
	v_writelane_b32 v254, s0, 62
	s_add_i32 s0, 0, 0x10038
	v_writelane_b32 v254, s0, 63
	s_add_i32 s0, 0, 0x1003c
	v_writelane_b32 v255, s0, 0
	v_writelane_b32 v255, s16, 1
	s_mov_b32 s15, 0xc3dc0000
	s_mov_b32 s1, 0x41000000
	v_writelane_b32 v255, s17, 2
	s_mov_b64 s[16:17], 0
	v_writelane_b32 v255, s16, 3
	s_mov_b32 s18, 0x3fd744fd
	s_mov_b32 s0, 0xbcb8aa3b
	v_writelane_b32 v255, s17, 4
	s_lshl_b64 s[16:17], s[74:75], 2
	v_writelane_b32 v255, s16, 5
	s_brev_b32 s14, 34
	s_nop 0
	v_writelane_b32 v255, s17, 6
	s_mov_b64 s[16:17], 0x40000
	v_writelane_b32 v255, s16, 7
	s_nop 1
	v_writelane_b32 v255, s17, 8
	v_writelane_b32 v255, s60, 9
	s_nop 1
	v_writelane_b32 v255, s61, 10
	v_writelane_b32 v255, s62, 11
	s_nop 1
	v_writelane_b32 v255, s63, 12
	s_branch .LBB0_12

.LBB0_1862:
	s_add_i32 s74, s74, 1
	s_mul_i32 s3, s74, s71
	s_mul_hi_u32 s36, s74, s19
	s_add_i32 s3, s36, s3
	s_mul_i32 s36, s74, s19
	s_add_u32 s36, s36, s2
	s_addc_u32 s37, s3, s73
	v_mov_b64_e32 v[0:1], 0xa00
	v_cmp_lt_i64_e64 s[40:41], s[36:37], v[0:1]
	v_mov_b64_e32 v[0:1], 0x9ff
	v_cmp_gt_i64_e32 vcc, s[36:37], v[0:1]
	s_cbranch_vccnz .LBB0_1864
	s_ashr_i32 s3, s36, 31
	s_lshr_b32 s3, s3, 29
	s_add_i32 s3, s36, s3
	s_ashr_i32 s37, s3, 3
	s_and_b32 s3, s3, -8
	s_sub_i32 s3, s36, s3
	s_cmp_lt_i32 s3, 0
	s_movk_i32 s36, 0x141
	s_cselect_b32 s36, s36, 0x140
	s_mul_i32 s3, s3, s36
	s_add_i32 s3, s3, s37
	s_ashr_i32 s36, s3, 31
	s_lshr_b32 s36, s36, 27
	s_add_i32 s36, s3, s36
	s_ashr_i32 s37, s36, 5
	s_lshl_b32 s37, s37, 3
	s_sub_i32 s38, 0x280, s37
	s_min_i32 s38, s38, 8
	s_abs_i32 s39, s38
	v_cvt_f32_u32_e32 v0, s39
	s_sub_i32 s59, 0, s39
	s_andn2_b32 s36, s36, 31
	s_sub_i32 s3, s3, s36
	v_rcp_iflag_f32_e32 v0, v0
	s_abs_i32 s36, s3
	s_xor_b32 s58, s3, s38
	s_ashr_i32 s58, s58, 31
	v_mul_f32_e32 v0, 0x4f7ffffe, v0
	v_cvt_u32_f32_e32 v0, v0
	s_nop 0
	v_readfirstlane_b32 s60, v0
	s_mul_i32 s59, s59, s60
	s_mul_hi_u32 s59, s60, s59
	s_add_i32 s60, s60, s59
	s_mul_hi_u32 s59, s36, s60
	s_mul_i32 s60, s59, s39
	s_sub_i32 s36, s36, s60
	s_add_i32 s61, s59, 1
	s_sub_i32 s60, s36, s39
	s_cmp_ge_u32 s36, s39
	s_cselect_b32 s59, s61, s59
	s_cselect_b32 s36, s60, s36
	s_add_i32 s60, s59, 1
	s_cmp_ge_u32 s36, s39
	s_cselect_b32 s36, s60, s59
	s_xor_b32 s36, s36, s58
	s_sub_i32 s58, s36, s58
	s_mul_i32 s36, s58, s38
	s_sub_i32 s3, s3, s36
	s_add_i32 s60, s37, s3
	s_mul_i32 s98, s60, 0xcccd
	s_lshr_b32 s98, s98, 22
	s_mul_i32 s98, s98, 0xa0
	s_addk_i32 s98, 0x4f
	s_sub_i32 s60, s98, s60
